# SwiGLU epilogue: also dropped the never-taken denormal guard around rsq (argument >= 1e-6)
# speedup vs baseline: 1.0079x; 1.0044x over previous
.LBB0_114:
	v_mov_b32_e32 v143, v218
	s_lshl_b32 s17, s24, 8
	s_add_i32 s17, s17, s47
	v_and_or_b32 v142, v143, 15, s17
	s_lshl_b32 s17, s25, 7
	v_lshrrev_b32_e32 v143, 1, v143
	v_and_or_b32 v143, v143, 24, s17
	v_or_b32_e32 v148, s48, v143
	v_ashrrev_i32_e32 v143, 31, v142
	v_lshl_add_u64 v[144:145], v[142:143], 3, s[10:11]
	global_load_dwordx2 v[146:147], v[144:145], off
	global_load_dwordx2 v[158:159], v[144:145], off offset:128
	global_load_dwordx2 v[160:161], v[144:145], off offset:256
	global_load_dwordx2 v[162:163], v[144:145], off offset:384
	global_load_dwordx2 v[164:165], v[144:145], off offset:1024
	global_load_dwordx2 v[166:167], v[144:145], off offset:1152
	global_load_dwordx2 v[168:169], v[144:145], off offset:1280
	global_load_dwordx2 v[170:171], v[144:145], off offset:1408
	v_ashrrev_i32_e32 v149, 31, v148
	s_waitcnt vmcnt(0)
	v_ffbh_u32_e32 v143, v147
	v_min_u32_e32 v143, 32, v143
	v_lshlrev_b64 v[146:147], v143, v[146:147]
	v_min_u32_e32 v146, 1, v146
	v_or_b32_e32 v146, v147, v146
	v_cvt_f32_u32_e32 v146, v146
	v_sub_u32_e32 v143, 32, v143
	v_ldexp_f32 v143, v146, v143
	v_fmamk_f32 v143, v143, 0x31800000, v219
	v_cmp_gt_f32_e32 vcc, s86, v143
	v_mul_f32_e32 v146, 0x4b800000, v143
	s_nop 0
	v_cndmask_b32_e32 v143, v143, v146, vcc
	v_rsq_f32_e32 v143, v143
	s_nop 0
	v_mul_f32_e32 v146, 0x45800000, v143
	v_cndmask_b32_e32 v154, v143, v146, vcc
	v_pk_mul_f32 v[126:127], v[126:127], v[154:155] op_sel_hi:[1,0]
	v_pk_mul_f32 v[118:119], v[118:119], v[154:155] op_sel_hi:[1,0]
	v_mul_f32_e32 v143, 0xbfb8aa3b, v126
	v_exp_f32_e32 v143, v143
	v_pk_mul_f32 v[120:121], v[120:121], v[154:155] op_sel_hi:[1,0]
	v_pk_mul_f32 v[122:123], v[122:123], v[154:155] op_sel_hi:[1,0]
	v_pk_mul_f32 v[114:115], v[114:115], v[154:155] op_sel_hi:[1,0]
	v_add_f32_e32 v143, 1.0, v143
	v_rcp_f32_e32 v156, v143
	v_mul_f32_e32 v143, 0xbfb8aa3b, v127
	v_exp_f32_e32 v143, v143
	v_mov_b64_e32 v[146:147], s[8:9]
	v_pk_mul_f32 v[116:117], v[116:117], v[154:155] op_sel_hi:[1,0]
	v_mad_i64_i32 v[150:151], s[24:25], v142, s83, v[146:147]
	v_add_f32_e32 v143, 1.0, v143
	v_rcp_f32_e32 v157, v143
	s_nop 0
	v_pk_mul_f32 v[126:127], v[126:127], v[156:157]
	s_nop 0
	v_pk_mul_f32 v[118:119], v[118:119], v[126:127]
	v_pk_mul_f32 v[126:127], v[128:129], v[154:155] op_sel_hi:[1,0]
	v_cvt_pk_bf16_f32 v118, v118, v119
	v_mul_f32_e32 v128, 0xbfb8aa3b, v126
	v_mul_f32_e32 v129, 0xbfb8aa3b, v127
	v_exp_f32_e32 v128, v128
	v_exp_f32_e32 v129, v129
	v_add_f32_e32 v128, 1.0, v128
	v_add_f32_e32 v129, 1.0, v129
	v_rcp_f32_e32 v128, v128
	v_rcp_f32_e32 v129, v129
	s_nop 0
	v_pk_mul_f32 v[126:127], v[126:127], v[128:129]
	s_nop 0
	v_pk_mul_f32 v[120:121], v[120:121], v[126:127]
	v_mul_f32_e32 v126, 0xbfb8aa3b, v122
	v_mul_f32_e32 v127, 0xbfb8aa3b, v123
	v_exp_f32_e32 v126, v126
	v_exp_f32_e32 v127, v127
	v_cvt_pk_bf16_f32 v119, v120, v121
	v_add_f32_e32 v126, 1.0, v126
	v_add_f32_e32 v127, 1.0, v127
	v_rcp_f32_e32 v126, v126
	v_rcp_f32_e32 v127, v127
	s_nop 0
	v_pk_mul_f32 v[122:123], v[122:123], v[126:127]
	s_nop 0
	v_pk_mul_f32 v[122:123], v[114:115], v[122:123]
	v_pk_mul_f32 v[114:115], v[124:125], v[154:155] op_sel_hi:[1,0]
	v_cvt_pk_bf16_f32 v120, v122, v123
	v_mul_f32_e32 v124, 0xbfb8aa3b, v114
	v_mul_f32_e32 v125, 0xbfb8aa3b, v115
	v_exp_f32_e32 v124, v124
	v_exp_f32_e32 v125, v125
	v_add_f32_e32 v124, 1.0, v124
	v_add_f32_e32 v125, 1.0, v125
	v_rcp_f32_e32 v124, v124
	v_rcp_f32_e32 v125, v125
	s_nop 0
	v_pk_mul_f32 v[114:115], v[114:115], v[124:125]
	s_nop 0
	v_pk_mul_f32 v[116:117], v[116:117], v[114:115]
	v_lshlrev_b64 v[114:115], 1, v[148:149]
	v_lshl_add_u64 v[124:125], v[150:151], 0, v[114:115]
	v_cvt_pk_bf16_f32 v121, v116, v117
	global_store_dwordx4 v[124:125], v[118:121], off
	v_mov_b32_e32 v192, 0xbfb8aa3b
	v_ffbh_u32_e32 v180, v159
	v_min_u32_e32 v180, 32, v180
	v_lshlrev_b64 v[178:179], v180, v[158:159]
	v_min_u32_e32 v178, 1, v178
	v_or_b32_e32 v178, v179, v178
	v_cvt_f32_u32_e32 v178, v178
	v_sub_u32_e32 v179, 32, v180
	v_ldexp_f32 v178, v178, v179
	v_fmamk_f32 v178, v178, 0x31800000, v219
	v_rsq_f32_e32 v178, v178
	v_or_b32_e32 v181, 16, v142
	v_mad_i64_i32 v[182:183], s[24:25], v181, s83, v[146:147]
	v_pk_mul_f32 v[110:111], v[110:111], v[178:179] op_sel_hi:[1,0]
	v_pk_mul_f32 v[112:113], v[112:113], v[178:179] op_sel_hi:[1,0]
	v_pk_mul_f32 v[106:107], v[106:107], v[178:179] op_sel_hi:[1,0]
	v_pk_mul_f32 v[108:109], v[108:109], v[178:179] op_sel_hi:[1,0]
	v_pk_mul_f32 v[102:103], v[102:103], v[178:179] op_sel_hi:[1,0]
	v_pk_mul_f32 v[104:105], v[104:105], v[178:179] op_sel_hi:[1,0]
	v_pk_mul_f32 v[98:99], v[98:99], v[178:179] op_sel_hi:[1,0]
	v_pk_mul_f32 v[100:101], v[100:101], v[178:179] op_sel_hi:[1,0]
	v_pk_mul_f32 v[188:189], v[110:111], v[192:193] op_sel_hi:[1,0]
	v_pk_mul_f32 v[190:191], v[112:113], v[192:193] op_sel_hi:[1,0]
	v_exp_f32_e32 v188, v188
	v_exp_f32_e32 v189, v189
	v_exp_f32_e32 v190, v190
	v_exp_f32_e32 v191, v191
	v_pk_add_f32 v[188:189], v[188:189], 1.0 op_sel_hi:[1,0]
	v_pk_add_f32 v[190:191], v[190:191], 1.0 op_sel_hi:[1,0]
	v_rcp_f32_e32 v188, v188
	v_rcp_f32_e32 v189, v189
	v_rcp_f32_e32 v190, v190
	v_rcp_f32_e32 v191, v191
	v_pk_mul_f32 v[110:111], v[110:111], v[188:189]
	v_pk_mul_f32 v[112:113], v[112:113], v[190:191]
	v_pk_mul_f32 v[102:103], v[102:103], v[110:111]
	v_pk_mul_f32 v[104:105], v[104:105], v[112:113]
	v_cvt_pk_bf16_f32 v184, v102, v103
	v_cvt_pk_bf16_f32 v185, v104, v105
	v_pk_mul_f32 v[188:189], v[106:107], v[192:193] op_sel_hi:[1,0]
	v_pk_mul_f32 v[190:191], v[108:109], v[192:193] op_sel_hi:[1,0]
	v_exp_f32_e32 v188, v188
	v_exp_f32_e32 v189, v189
	v_exp_f32_e32 v190, v190
	v_exp_f32_e32 v191, v191
	v_pk_add_f32 v[188:189], v[188:189], 1.0 op_sel_hi:[1,0]
	v_pk_add_f32 v[190:191], v[190:191], 1.0 op_sel_hi:[1,0]
	v_rcp_f32_e32 v188, v188
	v_rcp_f32_e32 v189, v189
	v_rcp_f32_e32 v190, v190
	v_rcp_f32_e32 v191, v191
	v_pk_mul_f32 v[106:107], v[106:107], v[188:189]
	v_pk_mul_f32 v[108:109], v[108:109], v[190:191]
	v_pk_mul_f32 v[98:99], v[98:99], v[106:107]
	v_pk_mul_f32 v[100:101], v[100:101], v[108:109]
	v_cvt_pk_bf16_f32 v186, v98, v99
	v_cvt_pk_bf16_f32 v187, v100, v101
	v_lshl_add_u64 v[182:183], v[182:183], 0, v[114:115]
	global_store_dwordx4 v[182:183], v[184:187], off
	v_ffbh_u32_e32 v180, v161
	v_min_u32_e32 v180, 32, v180
	v_lshlrev_b64 v[178:179], v180, v[160:161]
	v_min_u32_e32 v178, 1, v178
	v_or_b32_e32 v178, v179, v178
	v_cvt_f32_u32_e32 v178, v178
	v_sub_u32_e32 v179, 32, v180
	v_ldexp_f32 v178, v178, v179
	v_fmamk_f32 v178, v178, 0x31800000, v219
	v_rsq_f32_e32 v178, v178
	v_or_b32_e32 v181, 32, v142
	v_mad_i64_i32 v[182:183], s[24:25], v181, s83, v[146:147]
	v_pk_mul_f32 v[94:95], v[94:95], v[178:179] op_sel_hi:[1,0]
	v_pk_mul_f32 v[96:97], v[96:97], v[178:179] op_sel_hi:[1,0]
	v_pk_mul_f32 v[90:91], v[90:91], v[178:179] op_sel_hi:[1,0]
	v_pk_mul_f32 v[92:93], v[92:93], v[178:179] op_sel_hi:[1,0]
	v_pk_mul_f32 v[86:87], v[86:87], v[178:179] op_sel_hi:[1,0]
	v_pk_mul_f32 v[88:89], v[88:89], v[178:179] op_sel_hi:[1,0]
	v_pk_mul_f32 v[82:83], v[82:83], v[178:179] op_sel_hi:[1,0]
	v_pk_mul_f32 v[84:85], v[84:85], v[178:179] op_sel_hi:[1,0]
	v_pk_mul_f32 v[188:189], v[94:95], v[192:193] op_sel_hi:[1,0]
	v_pk_mul_f32 v[190:191], v[96:97], v[192:193] op_sel_hi:[1,0]
	v_exp_f32_e32 v188, v188
	v_exp_f32_e32 v189, v189
	v_exp_f32_e32 v190, v190
	v_exp_f32_e32 v191, v191
	v_pk_add_f32 v[188:189], v[188:189], 1.0 op_sel_hi:[1,0]
	v_pk_add_f32 v[190:191], v[190:191], 1.0 op_sel_hi:[1,0]
	v_rcp_f32_e32 v188, v188
	v_rcp_f32_e32 v189, v189
	v_rcp_f32_e32 v190, v190
	v_rcp_f32_e32 v191, v191
	v_pk_mul_f32 v[94:95], v[94:95], v[188:189]
	v_pk_mul_f32 v[96:97], v[96:97], v[190:191]
	v_pk_mul_f32 v[86:87], v[86:87], v[94:95]
	v_pk_mul_f32 v[88:89], v[88:89], v[96:97]
	v_cvt_pk_bf16_f32 v184, v86, v87
	v_cvt_pk_bf16_f32 v185, v88, v89
	v_pk_mul_f32 v[188:189], v[90:91], v[192:193] op_sel_hi:[1,0]
	v_pk_mul_f32 v[190:191], v[92:93], v[192:193] op_sel_hi:[1,0]
	v_exp_f32_e32 v188, v188
	v_exp_f32_e32 v189, v189
	v_exp_f32_e32 v190, v190
	v_exp_f32_e32 v191, v191
	v_pk_add_f32 v[188:189], v[188:189], 1.0 op_sel_hi:[1,0]
	v_pk_add_f32 v[190:191], v[190:191], 1.0 op_sel_hi:[1,0]
	v_rcp_f32_e32 v188, v188
	v_rcp_f32_e32 v189, v189
	v_rcp_f32_e32 v190, v190
	v_rcp_f32_e32 v191, v191
	v_pk_mul_f32 v[90:91], v[90:91], v[188:189]
	v_pk_mul_f32 v[92:93], v[92:93], v[190:191]
	v_pk_mul_f32 v[82:83], v[82:83], v[90:91]
	v_pk_mul_f32 v[84:85], v[84:85], v[92:93]
	v_cvt_pk_bf16_f32 v186, v82, v83
	v_cvt_pk_bf16_f32 v187, v84, v85
	v_lshl_add_u64 v[182:183], v[182:183], 0, v[114:115]
	global_store_dwordx4 v[182:183], v[184:187], off
	v_ffbh_u32_e32 v180, v163
	v_min_u32_e32 v180, 32, v180
	v_lshlrev_b64 v[178:179], v180, v[162:163]
	v_min_u32_e32 v178, 1, v178
	v_or_b32_e32 v178, v179, v178
	v_cvt_f32_u32_e32 v178, v178
	v_sub_u32_e32 v179, 32, v180
	v_ldexp_f32 v178, v178, v179
	v_fmamk_f32 v178, v178, 0x31800000, v219
	v_rsq_f32_e32 v178, v178
	v_or_b32_e32 v181, 48, v142
	v_mad_i64_i32 v[182:183], s[24:25], v181, s83, v[146:147]
	v_pk_mul_f32 v[78:79], v[78:79], v[178:179] op_sel_hi:[1,0]
	v_pk_mul_f32 v[80:81], v[80:81], v[178:179] op_sel_hi:[1,0]
	v_pk_mul_f32 v[74:75], v[74:75], v[178:179] op_sel_hi:[1,0]
	v_pk_mul_f32 v[76:77], v[76:77], v[178:179] op_sel_hi:[1,0]
	v_pk_mul_f32 v[70:71], v[70:71], v[178:179] op_sel_hi:[1,0]
	v_pk_mul_f32 v[72:73], v[72:73], v[178:179] op_sel_hi:[1,0]
	v_pk_mul_f32 v[66:67], v[66:67], v[178:179] op_sel_hi:[1,0]
	v_pk_mul_f32 v[68:69], v[68:69], v[178:179] op_sel_hi:[1,0]
	v_pk_mul_f32 v[188:189], v[78:79], v[192:193] op_sel_hi:[1,0]
	v_pk_mul_f32 v[190:191], v[80:81], v[192:193] op_sel_hi:[1,0]
	v_exp_f32_e32 v188, v188
	v_exp_f32_e32 v189, v189
	v_exp_f32_e32 v190, v190
	v_exp_f32_e32 v191, v191
	v_pk_add_f32 v[188:189], v[188:189], 1.0 op_sel_hi:[1,0]
	v_pk_add_f32 v[190:191], v[190:191], 1.0 op_sel_hi:[1,0]
	v_rcp_f32_e32 v188, v188
	v_rcp_f32_e32 v189, v189
	v_rcp_f32_e32 v190, v190
	v_rcp_f32_e32 v191, v191
	v_pk_mul_f32 v[78:79], v[78:79], v[188:189]
	v_pk_mul_f32 v[80:81], v[80:81], v[190:191]
	v_pk_mul_f32 v[70:71], v[70:71], v[78:79]
	v_pk_mul_f32 v[72:73], v[72:73], v[80:81]
	v_cvt_pk_bf16_f32 v184, v70, v71
	v_cvt_pk_bf16_f32 v185, v72, v73
	v_pk_mul_f32 v[188:189], v[74:75], v[192:193] op_sel_hi:[1,0]
	v_pk_mul_f32 v[190:191], v[76:77], v[192:193] op_sel_hi:[1,0]
	v_exp_f32_e32 v188, v188
	v_exp_f32_e32 v189, v189
	v_exp_f32_e32 v190, v190
	v_exp_f32_e32 v191, v191
	v_pk_add_f32 v[188:189], v[188:189], 1.0 op_sel_hi:[1,0]
	v_pk_add_f32 v[190:191], v[190:191], 1.0 op_sel_hi:[1,0]
	v_rcp_f32_e32 v188, v188
	v_rcp_f32_e32 v189, v189
	v_rcp_f32_e32 v190, v190
	v_rcp_f32_e32 v191, v191
	v_pk_mul_f32 v[74:75], v[74:75], v[188:189]
	v_pk_mul_f32 v[76:77], v[76:77], v[190:191]
	v_pk_mul_f32 v[66:67], v[66:67], v[74:75]
	v_pk_mul_f32 v[68:69], v[68:69], v[76:77]
	v_cvt_pk_bf16_f32 v186, v66, v67
	v_cvt_pk_bf16_f32 v187, v68, v69
	v_lshl_add_u64 v[182:183], v[182:183], 0, v[114:115]
	global_store_dwordx4 v[182:183], v[184:187], off
	v_ffbh_u32_e32 v180, v165
	v_min_u32_e32 v180, 32, v180
	v_lshlrev_b64 v[178:179], v180, v[164:165]
	v_min_u32_e32 v178, 1, v178
	v_or_b32_e32 v178, v179, v178
	v_cvt_f32_u32_e32 v178, v178
	v_sub_u32_e32 v179, 32, v180
	v_ldexp_f32 v178, v178, v179
	v_fmamk_f32 v178, v178, 0x31800000, v219
	v_rsq_f32_e32 v178, v178
	v_add_u32_e32 v181, 0x80, v142
	v_mad_i64_i32 v[182:183], s[24:25], v181, s83, v[146:147]
	v_pk_mul_f32 v[62:63], v[62:63], v[178:179] op_sel_hi:[1,0]
	v_pk_mul_f32 v[64:65], v[64:65], v[178:179] op_sel_hi:[1,0]
	v_pk_mul_f32 v[58:59], v[58:59], v[178:179] op_sel_hi:[1,0]
	v_pk_mul_f32 v[60:61], v[60:61], v[178:179] op_sel_hi:[1,0]
	v_pk_mul_f32 v[54:55], v[54:55], v[178:179] op_sel_hi:[1,0]
	v_pk_mul_f32 v[56:57], v[56:57], v[178:179] op_sel_hi:[1,0]
	v_pk_mul_f32 v[50:51], v[50:51], v[178:179] op_sel_hi:[1,0]
	v_pk_mul_f32 v[52:53], v[52:53], v[178:179] op_sel_hi:[1,0]
	v_pk_mul_f32 v[188:189], v[62:63], v[192:193] op_sel_hi:[1,0]
	v_pk_mul_f32 v[190:191], v[64:65], v[192:193] op_sel_hi:[1,0]
	v_exp_f32_e32 v188, v188
	v_exp_f32_e32 v189, v189
	v_exp_f32_e32 v190, v190
	v_exp_f32_e32 v191, v191
	v_pk_add_f32 v[188:189], v[188:189], 1.0 op_sel_hi:[1,0]
	v_pk_add_f32 v[190:191], v[190:191], 1.0 op_sel_hi:[1,0]
	v_rcp_f32_e32 v188, v188
	v_rcp_f32_e32 v189, v189
	v_rcp_f32_e32 v190, v190
	v_rcp_f32_e32 v191, v191
	v_pk_mul_f32 v[62:63], v[62:63], v[188:189]
	v_pk_mul_f32 v[64:65], v[64:65], v[190:191]
	v_pk_mul_f32 v[54:55], v[54:55], v[62:63]
	v_pk_mul_f32 v[56:57], v[56:57], v[64:65]
	v_cvt_pk_bf16_f32 v184, v54, v55
	v_cvt_pk_bf16_f32 v185, v56, v57
	v_pk_mul_f32 v[188:189], v[58:59], v[192:193] op_sel_hi:[1,0]
	v_pk_mul_f32 v[190:191], v[60:61], v[192:193] op_sel_hi:[1,0]
	v_exp_f32_e32 v188, v188
	v_exp_f32_e32 v189, v189
	v_exp_f32_e32 v190, v190
	v_exp_f32_e32 v191, v191
	v_pk_add_f32 v[188:189], v[188:189], 1.0 op_sel_hi:[1,0]
	v_pk_add_f32 v[190:191], v[190:191], 1.0 op_sel_hi:[1,0]
	v_rcp_f32_e32 v188, v188
	v_rcp_f32_e32 v189, v189
	v_rcp_f32_e32 v190, v190
	v_rcp_f32_e32 v191, v191
	v_pk_mul_f32 v[58:59], v[58:59], v[188:189]
	v_pk_mul_f32 v[60:61], v[60:61], v[190:191]
	v_pk_mul_f32 v[50:51], v[50:51], v[58:59]
	v_pk_mul_f32 v[52:53], v[52:53], v[60:61]
	v_cvt_pk_bf16_f32 v186, v50, v51
	v_cvt_pk_bf16_f32 v187, v52, v53
	v_lshl_add_u64 v[182:183], v[182:183], 0, v[114:115]
	global_store_dwordx4 v[182:183], v[184:187], off
	v_ffbh_u32_e32 v180, v167
	v_min_u32_e32 v180, 32, v180
	v_lshlrev_b64 v[178:179], v180, v[166:167]
	v_min_u32_e32 v178, 1, v178
	v_or_b32_e32 v178, v179, v178
	v_cvt_f32_u32_e32 v178, v178
	v_sub_u32_e32 v179, 32, v180
	v_ldexp_f32 v178, v178, v179
	v_fmamk_f32 v178, v178, 0x31800000, v219
	v_rsq_f32_e32 v178, v178
	v_add_u32_e32 v181, 0x90, v142
	v_mad_i64_i32 v[182:183], s[24:25], v181, s83, v[146:147]
	v_pk_mul_f32 v[46:47], v[46:47], v[178:179] op_sel_hi:[1,0]
	v_pk_mul_f32 v[48:49], v[48:49], v[178:179] op_sel_hi:[1,0]
	v_pk_mul_f32 v[42:43], v[42:43], v[178:179] op_sel_hi:[1,0]
	v_pk_mul_f32 v[44:45], v[44:45], v[178:179] op_sel_hi:[1,0]
	v_pk_mul_f32 v[38:39], v[38:39], v[178:179] op_sel_hi:[1,0]
	v_pk_mul_f32 v[40:41], v[40:41], v[178:179] op_sel_hi:[1,0]
	v_pk_mul_f32 v[34:35], v[34:35], v[178:179] op_sel_hi:[1,0]
	v_pk_mul_f32 v[36:37], v[36:37], v[178:179] op_sel_hi:[1,0]
	v_pk_mul_f32 v[188:189], v[46:47], v[192:193] op_sel_hi:[1,0]
	v_pk_mul_f32 v[190:191], v[48:49], v[192:193] op_sel_hi:[1,0]
	v_exp_f32_e32 v188, v188
	v_exp_f32_e32 v189, v189
	v_exp_f32_e32 v190, v190
	v_exp_f32_e32 v191, v191
	v_pk_add_f32 v[188:189], v[188:189], 1.0 op_sel_hi:[1,0]
	v_pk_add_f32 v[190:191], v[190:191], 1.0 op_sel_hi:[1,0]
	v_rcp_f32_e32 v188, v188
	v_rcp_f32_e32 v189, v189
	v_rcp_f32_e32 v190, v190
	v_rcp_f32_e32 v191, v191
	v_pk_mul_f32 v[46:47], v[46:47], v[188:189]
	v_pk_mul_f32 v[48:49], v[48:49], v[190:191]
	v_pk_mul_f32 v[38:39], v[38:39], v[46:47]
	v_pk_mul_f32 v[40:41], v[40:41], v[48:49]
	v_cvt_pk_bf16_f32 v184, v38, v39
	v_cvt_pk_bf16_f32 v185, v40, v41
	v_pk_mul_f32 v[188:189], v[42:43], v[192:193] op_sel_hi:[1,0]
	v_pk_mul_f32 v[190:191], v[44:45], v[192:193] op_sel_hi:[1,0]
	v_exp_f32_e32 v188, v188
	v_exp_f32_e32 v189, v189
	v_exp_f32_e32 v190, v190
	v_exp_f32_e32 v191, v191
	v_pk_add_f32 v[188:189], v[188:189], 1.0 op_sel_hi:[1,0]
	v_pk_add_f32 v[190:191], v[190:191], 1.0 op_sel_hi:[1,0]
	v_rcp_f32_e32 v188, v188
	v_rcp_f32_e32 v189, v189
	v_rcp_f32_e32 v190, v190
	v_rcp_f32_e32 v191, v191
	v_pk_mul_f32 v[42:43], v[42:43], v[188:189]
	v_pk_mul_f32 v[44:45], v[44:45], v[190:191]
	v_pk_mul_f32 v[34:35], v[34:35], v[42:43]
	v_pk_mul_f32 v[36:37], v[36:37], v[44:45]
	v_cvt_pk_bf16_f32 v186, v34, v35
	v_cvt_pk_bf16_f32 v187, v36, v37
	v_lshl_add_u64 v[182:183], v[182:183], 0, v[114:115]
	global_store_dwordx4 v[182:183], v[184:187], off
	v_ffbh_u32_e32 v180, v169
	v_min_u32_e32 v180, 32, v180
	v_lshlrev_b64 v[178:179], v180, v[168:169]
	v_min_u32_e32 v178, 1, v178
	v_or_b32_e32 v178, v179, v178
	v_cvt_f32_u32_e32 v178, v178
	v_sub_u32_e32 v179, 32, v180
	v_ldexp_f32 v178, v178, v179
	v_fmamk_f32 v178, v178, 0x31800000, v219
	v_rsq_f32_e32 v178, v178
	v_add_u32_e32 v181, 0xa0, v142
	v_mad_i64_i32 v[182:183], s[24:25], v181, s83, v[146:147]
	v_pk_mul_f32 v[30:31], v[30:31], v[178:179] op_sel_hi:[1,0]
	v_pk_mul_f32 v[32:33], v[32:33], v[178:179] op_sel_hi:[1,0]
	v_pk_mul_f32 v[26:27], v[26:27], v[178:179] op_sel_hi:[1,0]
	v_pk_mul_f32 v[28:29], v[28:29], v[178:179] op_sel_hi:[1,0]
	v_pk_mul_f32 v[22:23], v[22:23], v[178:179] op_sel_hi:[1,0]
	v_pk_mul_f32 v[24:25], v[24:25], v[178:179] op_sel_hi:[1,0]
	v_pk_mul_f32 v[18:19], v[18:19], v[178:179] op_sel_hi:[1,0]
	v_pk_mul_f32 v[20:21], v[20:21], v[178:179] op_sel_hi:[1,0]
	v_pk_mul_f32 v[188:189], v[30:31], v[192:193] op_sel_hi:[1,0]
	v_pk_mul_f32 v[190:191], v[32:33], v[192:193] op_sel_hi:[1,0]
	v_exp_f32_e32 v188, v188
	v_exp_f32_e32 v189, v189
	v_exp_f32_e32 v190, v190
	v_exp_f32_e32 v191, v191
	v_pk_add_f32 v[188:189], v[188:189], 1.0 op_sel_hi:[1,0]
	v_pk_add_f32 v[190:191], v[190:191], 1.0 op_sel_hi:[1,0]
	v_rcp_f32_e32 v188, v188
	v_rcp_f32_e32 v189, v189
	v_rcp_f32_e32 v190, v190
	v_rcp_f32_e32 v191, v191
	v_pk_mul_f32 v[30:31], v[30:31], v[188:189]
	v_pk_mul_f32 v[32:33], v[32:33], v[190:191]
	v_pk_mul_f32 v[22:23], v[22:23], v[30:31]
	v_pk_mul_f32 v[24:25], v[24:25], v[32:33]
	v_cvt_pk_bf16_f32 v184, v22, v23
	v_cvt_pk_bf16_f32 v185, v24, v25
	v_pk_mul_f32 v[188:189], v[26:27], v[192:193] op_sel_hi:[1,0]
	v_pk_mul_f32 v[190:191], v[28:29], v[192:193] op_sel_hi:[1,0]
	v_exp_f32_e32 v188, v188
	v_exp_f32_e32 v189, v189
	v_exp_f32_e32 v190, v190
	v_exp_f32_e32 v191, v191
	v_pk_add_f32 v[188:189], v[188:189], 1.0 op_sel_hi:[1,0]
	v_pk_add_f32 v[190:191], v[190:191], 1.0 op_sel_hi:[1,0]
	v_rcp_f32_e32 v188, v188
	v_rcp_f32_e32 v189, v189
	v_rcp_f32_e32 v190, v190
	v_rcp_f32_e32 v191, v191
	v_pk_mul_f32 v[26:27], v[26:27], v[188:189]
	v_pk_mul_f32 v[28:29], v[28:29], v[190:191]
	v_pk_mul_f32 v[18:19], v[18:19], v[26:27]
	v_pk_mul_f32 v[20:21], v[20:21], v[28:29]
	v_cvt_pk_bf16_f32 v186, v18, v19
	v_cvt_pk_bf16_f32 v187, v20, v21
	v_lshl_add_u64 v[182:183], v[182:183], 0, v[114:115]
	global_store_dwordx4 v[182:183], v[184:187], off
	v_ffbh_u32_e32 v180, v171
	v_min_u32_e32 v180, 32, v180
	v_lshlrev_b64 v[178:179], v180, v[170:171]
	v_min_u32_e32 v178, 1, v178
	v_or_b32_e32 v178, v179, v178
	v_cvt_f32_u32_e32 v178, v178
	v_sub_u32_e32 v179, 32, v180
	v_ldexp_f32 v178, v178, v179
	v_fmamk_f32 v178, v178, 0x31800000, v219
	v_rsq_f32_e32 v178, v178
	v_add_u32_e32 v181, 0xb0, v142
	v_mad_i64_i32 v[182:183], s[24:25], v181, s83, v[146:147]
	s_andn2_b64 vcc, exec, s[2:3]
	v_pk_mul_f32 v[14:15], v[14:15], v[178:179] op_sel_hi:[1,0]
	v_pk_mul_f32 v[16:17], v[16:17], v[178:179] op_sel_hi:[1,0]
	v_pk_mul_f32 v[10:11], v[10:11], v[178:179] op_sel_hi:[1,0]
	v_pk_mul_f32 v[12:13], v[12:13], v[178:179] op_sel_hi:[1,0]
	v_pk_mul_f32 v[6:7], v[6:7], v[178:179] op_sel_hi:[1,0]
	v_pk_mul_f32 v[8:9], v[8:9], v[178:179] op_sel_hi:[1,0]
	v_pk_mul_f32 v[2:3], v[2:3], v[178:179] op_sel_hi:[1,0]
	v_pk_mul_f32 v[4:5], v[4:5], v[178:179] op_sel_hi:[1,0]
	s_mov_b64 s[24:25], -1
	v_pk_mul_f32 v[188:189], v[14:15], v[192:193] op_sel_hi:[1,0]
	v_pk_mul_f32 v[190:191], v[16:17], v[192:193] op_sel_hi:[1,0]
	v_exp_f32_e32 v188, v188
	v_exp_f32_e32 v189, v189
	v_exp_f32_e32 v190, v190
	v_exp_f32_e32 v191, v191
	v_pk_add_f32 v[188:189], v[188:189], 1.0 op_sel_hi:[1,0]
	v_pk_add_f32 v[190:191], v[190:191], 1.0 op_sel_hi:[1,0]
	v_rcp_f32_e32 v188, v188
	v_rcp_f32_e32 v189, v189
	v_rcp_f32_e32 v190, v190
	v_rcp_f32_e32 v191, v191
	v_pk_mul_f32 v[14:15], v[14:15], v[188:189]
	v_pk_mul_f32 v[16:17], v[16:17], v[190:191]
	v_pk_mul_f32 v[6:7], v[6:7], v[14:15]
	v_pk_mul_f32 v[8:9], v[8:9], v[16:17]
	v_cvt_pk_bf16_f32 v184, v6, v7
	v_cvt_pk_bf16_f32 v185, v8, v9
	v_pk_mul_f32 v[188:189], v[10:11], v[192:193] op_sel_hi:[1,0]
	v_pk_mul_f32 v[190:191], v[12:13], v[192:193] op_sel_hi:[1,0]
	v_exp_f32_e32 v188, v188
	v_exp_f32_e32 v189, v189
	v_exp_f32_e32 v190, v190
	v_exp_f32_e32 v191, v191
	v_pk_add_f32 v[188:189], v[188:189], 1.0 op_sel_hi:[1,0]
	v_pk_add_f32 v[190:191], v[190:191], 1.0 op_sel_hi:[1,0]
	v_rcp_f32_e32 v188, v188
	v_rcp_f32_e32 v189, v189
	v_rcp_f32_e32 v190, v190
	v_rcp_f32_e32 v191, v191
	v_pk_mul_f32 v[10:11], v[10:11], v[188:189]
	v_pk_mul_f32 v[12:13], v[12:13], v[190:191]
	v_pk_mul_f32 v[2:3], v[2:3], v[10:11]
	v_pk_mul_f32 v[4:5], v[4:5], v[12:13]
	v_cvt_pk_bf16_f32 v186, v2, v3
	v_cvt_pk_bf16_f32 v187, v4, v5
	v_lshl_add_u64 v[182:183], v[182:183], 0, v[114:115]
	global_store_dwordx4 v[182:183], v[184:187], off
	s_cbranch_vccnz .LBB0_107
	s_andn2_b64 vcc, exec, s[6:7]
	s_cbranch_vccnz .LBB0_106
	s_barrier
	s_branch .LBB0_106

.Lsw_skip_ffn2up:
	v_ashrrev_i32_e32 v149, 31, v148
	s_waitcnt vmcnt(0)
	v_ffbh_u32_e32 v143, v147
	v_min_u32_e32 v143, 32, v143
	v_lshlrev_b64 v[146:147], v143, v[146:147]
	v_min_u32_e32 v146, 1, v146
	v_or_b32_e32 v146, v147, v146
	v_cvt_f32_u32_e32 v146, v146
	v_sub_u32_e32 v143, 32, v143
	v_ldexp_f32 v143, v146, v143
	v_fmamk_f32 v143, v143, 0x31800000, v219
	v_cmp_gt_f32_e32 vcc, s86, v143
	v_mul_f32_e32 v146, 0x4b800000, v143
	s_nop 0
	v_cndmask_b32_e32 v143, v143, v146, vcc
	v_rsq_f32_e32 v143, v143
	s_nop 0
	v_mul_f32_e32 v146, 0x45800000, v143
	v_cndmask_b32_e32 v154, v143, v146, vcc
	v_pk_mul_f32 v[126:127], v[126:127], v[154:155] op_sel_hi:[1,0]
	v_pk_mul_f32 v[118:119], v[118:119], v[154:155] op_sel_hi:[1,0]
	v_mul_f32_e32 v143, 0xbfb8aa3b, v126
	v_exp_f32_e32 v143, v143
	v_pk_mul_f32 v[120:121], v[120:121], v[154:155] op_sel_hi:[1,0]
	v_pk_mul_f32 v[122:123], v[122:123], v[154:155] op_sel_hi:[1,0]
	v_pk_mul_f32 v[114:115], v[114:115], v[154:155] op_sel_hi:[1,0]
	v_add_f32_e32 v143, 1.0, v143
	v_rcp_f32_e32 v156, v143
	v_mul_f32_e32 v143, 0xbfb8aa3b, v127
	v_exp_f32_e32 v143, v143
	v_mov_b64_e32 v[146:147], s[8:9]
	v_pk_mul_f32 v[116:117], v[116:117], v[154:155] op_sel_hi:[1,0]
	v_mad_i64_i32 v[150:151], s[22:23], v142, s83, v[146:147]
	v_add_f32_e32 v143, 1.0, v143
	v_rcp_f32_e32 v157, v143
	s_nop 0
	v_pk_mul_f32 v[126:127], v[126:127], v[156:157]
	s_nop 0
	v_pk_mul_f32 v[118:119], v[118:119], v[126:127]
	v_pk_mul_f32 v[126:127], v[128:129], v[154:155] op_sel_hi:[1,0]
	v_cvt_pk_bf16_f32 v118, v118, v119
	v_mul_f32_e32 v128, 0xbfb8aa3b, v126
	v_mul_f32_e32 v129, 0xbfb8aa3b, v127
	v_exp_f32_e32 v128, v128
	v_exp_f32_e32 v129, v129
	v_add_f32_e32 v128, 1.0, v128
	v_add_f32_e32 v129, 1.0, v129
	v_rcp_f32_e32 v128, v128
	v_rcp_f32_e32 v129, v129
	s_nop 0
	v_pk_mul_f32 v[126:127], v[126:127], v[128:129]
	s_nop 0
	v_pk_mul_f32 v[120:121], v[120:121], v[126:127]
	v_mul_f32_e32 v126, 0xbfb8aa3b, v122
	v_mul_f32_e32 v127, 0xbfb8aa3b, v123
	v_exp_f32_e32 v126, v126
	v_exp_f32_e32 v127, v127
	v_cvt_pk_bf16_f32 v119, v120, v121
	v_add_f32_e32 v126, 1.0, v126
	v_add_f32_e32 v127, 1.0, v127
	v_rcp_f32_e32 v126, v126
	v_rcp_f32_e32 v127, v127
	s_nop 0
	v_pk_mul_f32 v[122:123], v[122:123], v[126:127]
	s_nop 0
	v_pk_mul_f32 v[122:123], v[114:115], v[122:123]
	v_pk_mul_f32 v[114:115], v[124:125], v[154:155] op_sel_hi:[1,0]
	v_cvt_pk_bf16_f32 v120, v122, v123
	v_mul_f32_e32 v124, 0xbfb8aa3b, v114
	v_mul_f32_e32 v125, 0xbfb8aa3b, v115
	v_exp_f32_e32 v124, v124
	v_exp_f32_e32 v125, v125
	v_add_f32_e32 v124, 1.0, v124
	v_add_f32_e32 v125, 1.0, v125
	v_rcp_f32_e32 v124, v124
	v_rcp_f32_e32 v125, v125
	s_nop 0
	v_pk_mul_f32 v[114:115], v[114:115], v[124:125]
	s_nop 0
	v_pk_mul_f32 v[116:117], v[116:117], v[114:115]
	v_lshlrev_b64 v[114:115], 1, v[148:149]
	v_lshl_add_u64 v[124:125], v[150:151], 0, v[114:115]
	v_cvt_pk_bf16_f32 v121, v116, v117
	global_store_dwordx4 v[124:125], v[118:121], off
	v_mov_b32_e32 v192, 0xbfb8aa3b
	v_ffbh_u32_e32 v180, v159
	v_min_u32_e32 v180, 32, v180
	v_lshlrev_b64 v[178:179], v180, v[158:159]
	v_min_u32_e32 v178, 1, v178
	v_or_b32_e32 v178, v179, v178
	v_cvt_f32_u32_e32 v178, v178
	v_sub_u32_e32 v179, 32, v180
	v_ldexp_f32 v178, v178, v179
	v_fmamk_f32 v178, v178, 0x31800000, v219
	v_rsq_f32_e32 v178, v178
	v_or_b32_e32 v181, 16, v142
	v_mad_i64_i32 v[182:183], s[22:23], v181, s83, v[146:147]
	v_pk_mul_f32 v[110:111], v[110:111], v[178:179] op_sel_hi:[1,0]
	v_pk_mul_f32 v[112:113], v[112:113], v[178:179] op_sel_hi:[1,0]
	v_pk_mul_f32 v[106:107], v[106:107], v[178:179] op_sel_hi:[1,0]
	v_pk_mul_f32 v[108:109], v[108:109], v[178:179] op_sel_hi:[1,0]
	v_pk_mul_f32 v[102:103], v[102:103], v[178:179] op_sel_hi:[1,0]
	v_pk_mul_f32 v[104:105], v[104:105], v[178:179] op_sel_hi:[1,0]
	v_pk_mul_f32 v[98:99], v[98:99], v[178:179] op_sel_hi:[1,0]
	v_pk_mul_f32 v[100:101], v[100:101], v[178:179] op_sel_hi:[1,0]
	v_pk_mul_f32 v[188:189], v[110:111], v[192:193] op_sel_hi:[1,0]
	v_pk_mul_f32 v[190:191], v[112:113], v[192:193] op_sel_hi:[1,0]
	v_exp_f32_e32 v188, v188
	v_exp_f32_e32 v189, v189
	v_exp_f32_e32 v190, v190
	v_exp_f32_e32 v191, v191
	v_pk_add_f32 v[188:189], v[188:189], 1.0 op_sel_hi:[1,0]
	v_pk_add_f32 v[190:191], v[190:191], 1.0 op_sel_hi:[1,0]
	v_rcp_f32_e32 v188, v188
	v_rcp_f32_e32 v189, v189
	v_rcp_f32_e32 v190, v190
	v_rcp_f32_e32 v191, v191
	v_pk_mul_f32 v[110:111], v[110:111], v[188:189]
	v_pk_mul_f32 v[112:113], v[112:113], v[190:191]
	v_pk_mul_f32 v[102:103], v[102:103], v[110:111]
	v_pk_mul_f32 v[104:105], v[104:105], v[112:113]
	v_cvt_pk_bf16_f32 v184, v102, v103
	v_cvt_pk_bf16_f32 v185, v104, v105
	v_pk_mul_f32 v[188:189], v[106:107], v[192:193] op_sel_hi:[1,0]
	v_pk_mul_f32 v[190:191], v[108:109], v[192:193] op_sel_hi:[1,0]
	v_exp_f32_e32 v188, v188
	v_exp_f32_e32 v189, v189
	v_exp_f32_e32 v190, v190
	v_exp_f32_e32 v191, v191
	v_pk_add_f32 v[188:189], v[188:189], 1.0 op_sel_hi:[1,0]
	v_pk_add_f32 v[190:191], v[190:191], 1.0 op_sel_hi:[1,0]
	v_rcp_f32_e32 v188, v188
	v_rcp_f32_e32 v189, v189
	v_rcp_f32_e32 v190, v190
	v_rcp_f32_e32 v191, v191
	v_pk_mul_f32 v[106:107], v[106:107], v[188:189]
	v_pk_mul_f32 v[108:109], v[108:109], v[190:191]
	v_pk_mul_f32 v[98:99], v[98:99], v[106:107]
	v_pk_mul_f32 v[100:101], v[100:101], v[108:109]
	v_cvt_pk_bf16_f32 v186, v98, v99
	v_cvt_pk_bf16_f32 v187, v100, v101
	v_lshl_add_u64 v[182:183], v[182:183], 0, v[114:115]
	global_store_dwordx4 v[182:183], v[184:187], off
	v_ffbh_u32_e32 v180, v161
	v_min_u32_e32 v180, 32, v180
	v_lshlrev_b64 v[178:179], v180, v[160:161]
	v_min_u32_e32 v178, 1, v178
	v_or_b32_e32 v178, v179, v178
	v_cvt_f32_u32_e32 v178, v178
	v_sub_u32_e32 v179, 32, v180
	v_ldexp_f32 v178, v178, v179
	v_fmamk_f32 v178, v178, 0x31800000, v219
	v_rsq_f32_e32 v178, v178
	v_or_b32_e32 v181, 32, v142
	v_mad_i64_i32 v[182:183], s[22:23], v181, s83, v[146:147]
	v_pk_mul_f32 v[94:95], v[94:95], v[178:179] op_sel_hi:[1,0]
	v_pk_mul_f32 v[96:97], v[96:97], v[178:179] op_sel_hi:[1,0]
	v_pk_mul_f32 v[90:91], v[90:91], v[178:179] op_sel_hi:[1,0]
	v_pk_mul_f32 v[92:93], v[92:93], v[178:179] op_sel_hi:[1,0]
	v_pk_mul_f32 v[86:87], v[86:87], v[178:179] op_sel_hi:[1,0]
	v_pk_mul_f32 v[88:89], v[88:89], v[178:179] op_sel_hi:[1,0]
	v_pk_mul_f32 v[82:83], v[82:83], v[178:179] op_sel_hi:[1,0]
	v_pk_mul_f32 v[84:85], v[84:85], v[178:179] op_sel_hi:[1,0]
	v_pk_mul_f32 v[188:189], v[94:95], v[192:193] op_sel_hi:[1,0]
	v_pk_mul_f32 v[190:191], v[96:97], v[192:193] op_sel_hi:[1,0]
	v_exp_f32_e32 v188, v188
	v_exp_f32_e32 v189, v189
	v_exp_f32_e32 v190, v190
	v_exp_f32_e32 v191, v191
	v_pk_add_f32 v[188:189], v[188:189], 1.0 op_sel_hi:[1,0]
	v_pk_add_f32 v[190:191], v[190:191], 1.0 op_sel_hi:[1,0]
	v_rcp_f32_e32 v188, v188
	v_rcp_f32_e32 v189, v189
	v_rcp_f32_e32 v190, v190
	v_rcp_f32_e32 v191, v191
	v_pk_mul_f32 v[94:95], v[94:95], v[188:189]
	v_pk_mul_f32 v[96:97], v[96:97], v[190:191]
	v_pk_mul_f32 v[86:87], v[86:87], v[94:95]
	v_pk_mul_f32 v[88:89], v[88:89], v[96:97]
	v_cvt_pk_bf16_f32 v184, v86, v87
	v_cvt_pk_bf16_f32 v185, v88, v89
	v_pk_mul_f32 v[188:189], v[90:91], v[192:193] op_sel_hi:[1,0]
	v_pk_mul_f32 v[190:191], v[92:93], v[192:193] op_sel_hi:[1,0]
	v_exp_f32_e32 v188, v188
	v_exp_f32_e32 v189, v189
	v_exp_f32_e32 v190, v190
	v_exp_f32_e32 v191, v191
	v_pk_add_f32 v[188:189], v[188:189], 1.0 op_sel_hi:[1,0]
	v_pk_add_f32 v[190:191], v[190:191], 1.0 op_sel_hi:[1,0]
	v_rcp_f32_e32 v188, v188
	v_rcp_f32_e32 v189, v189
	v_rcp_f32_e32 v190, v190
	v_rcp_f32_e32 v191, v191
	v_pk_mul_f32 v[90:91], v[90:91], v[188:189]
	v_pk_mul_f32 v[92:93], v[92:93], v[190:191]
	v_pk_mul_f32 v[82:83], v[82:83], v[90:91]
	v_pk_mul_f32 v[84:85], v[84:85], v[92:93]
	v_cvt_pk_bf16_f32 v186, v82, v83
	v_cvt_pk_bf16_f32 v187, v84, v85
	v_lshl_add_u64 v[182:183], v[182:183], 0, v[114:115]
	global_store_dwordx4 v[182:183], v[184:187], off
	v_ffbh_u32_e32 v180, v163
	v_min_u32_e32 v180, 32, v180
	v_lshlrev_b64 v[178:179], v180, v[162:163]
	v_min_u32_e32 v178, 1, v178
	v_or_b32_e32 v178, v179, v178
	v_cvt_f32_u32_e32 v178, v178
	v_sub_u32_e32 v179, 32, v180
	v_ldexp_f32 v178, v178, v179
	v_fmamk_f32 v178, v178, 0x31800000, v219
	v_rsq_f32_e32 v178, v178
	v_or_b32_e32 v181, 48, v142
	v_mad_i64_i32 v[182:183], s[22:23], v181, s83, v[146:147]
	v_pk_mul_f32 v[78:79], v[78:79], v[178:179] op_sel_hi:[1,0]
	v_pk_mul_f32 v[80:81], v[80:81], v[178:179] op_sel_hi:[1,0]
	v_pk_mul_f32 v[74:75], v[74:75], v[178:179] op_sel_hi:[1,0]
	v_pk_mul_f32 v[76:77], v[76:77], v[178:179] op_sel_hi:[1,0]
	v_pk_mul_f32 v[70:71], v[70:71], v[178:179] op_sel_hi:[1,0]
	v_pk_mul_f32 v[72:73], v[72:73], v[178:179] op_sel_hi:[1,0]
	v_pk_mul_f32 v[66:67], v[66:67], v[178:179] op_sel_hi:[1,0]
	v_pk_mul_f32 v[68:69], v[68:69], v[178:179] op_sel_hi:[1,0]
	v_pk_mul_f32 v[188:189], v[78:79], v[192:193] op_sel_hi:[1,0]
	v_pk_mul_f32 v[190:191], v[80:81], v[192:193] op_sel_hi:[1,0]
	v_exp_f32_e32 v188, v188
	v_exp_f32_e32 v189, v189
	v_exp_f32_e32 v190, v190
	v_exp_f32_e32 v191, v191
	v_pk_add_f32 v[188:189], v[188:189], 1.0 op_sel_hi:[1,0]
	v_pk_add_f32 v[190:191], v[190:191], 1.0 op_sel_hi:[1,0]
	v_rcp_f32_e32 v188, v188
	v_rcp_f32_e32 v189, v189
	v_rcp_f32_e32 v190, v190
	v_rcp_f32_e32 v191, v191
	v_pk_mul_f32 v[78:79], v[78:79], v[188:189]
	v_pk_mul_f32 v[80:81], v[80:81], v[190:191]
	v_pk_mul_f32 v[70:71], v[70:71], v[78:79]
	v_pk_mul_f32 v[72:73], v[72:73], v[80:81]
	v_cvt_pk_bf16_f32 v184, v70, v71
	v_cvt_pk_bf16_f32 v185, v72, v73
	v_pk_mul_f32 v[188:189], v[74:75], v[192:193] op_sel_hi:[1,0]
	v_pk_mul_f32 v[190:191], v[76:77], v[192:193] op_sel_hi:[1,0]
	v_exp_f32_e32 v188, v188
	v_exp_f32_e32 v189, v189
	v_exp_f32_e32 v190, v190
	v_exp_f32_e32 v191, v191
	v_pk_add_f32 v[188:189], v[188:189], 1.0 op_sel_hi:[1,0]
	v_pk_add_f32 v[190:191], v[190:191], 1.0 op_sel_hi:[1,0]
	v_rcp_f32_e32 v188, v188
	v_rcp_f32_e32 v189, v189
	v_rcp_f32_e32 v190, v190
	v_rcp_f32_e32 v191, v191
	v_pk_mul_f32 v[74:75], v[74:75], v[188:189]
	v_pk_mul_f32 v[76:77], v[76:77], v[190:191]
	v_pk_mul_f32 v[66:67], v[66:67], v[74:75]
	v_pk_mul_f32 v[68:69], v[68:69], v[76:77]
	v_cvt_pk_bf16_f32 v186, v66, v67
	v_cvt_pk_bf16_f32 v187, v68, v69
	v_lshl_add_u64 v[182:183], v[182:183], 0, v[114:115]
	global_store_dwordx4 v[182:183], v[184:187], off
	v_ffbh_u32_e32 v180, v165
	v_min_u32_e32 v180, 32, v180
	v_lshlrev_b64 v[178:179], v180, v[164:165]
	v_min_u32_e32 v178, 1, v178
	v_or_b32_e32 v178, v179, v178
	v_cvt_f32_u32_e32 v178, v178
	v_sub_u32_e32 v179, 32, v180
	v_ldexp_f32 v178, v178, v179
	v_fmamk_f32 v178, v178, 0x31800000, v219
	v_rsq_f32_e32 v178, v178
	v_add_u32_e32 v181, 0x80, v142
	v_mad_i64_i32 v[182:183], s[22:23], v181, s83, v[146:147]
	v_pk_mul_f32 v[62:63], v[62:63], v[178:179] op_sel_hi:[1,0]
	v_pk_mul_f32 v[64:65], v[64:65], v[178:179] op_sel_hi:[1,0]
	v_pk_mul_f32 v[58:59], v[58:59], v[178:179] op_sel_hi:[1,0]
	v_pk_mul_f32 v[60:61], v[60:61], v[178:179] op_sel_hi:[1,0]
	v_pk_mul_f32 v[54:55], v[54:55], v[178:179] op_sel_hi:[1,0]
	v_pk_mul_f32 v[56:57], v[56:57], v[178:179] op_sel_hi:[1,0]
	v_pk_mul_f32 v[50:51], v[50:51], v[178:179] op_sel_hi:[1,0]
	v_pk_mul_f32 v[52:53], v[52:53], v[178:179] op_sel_hi:[1,0]
	v_pk_mul_f32 v[188:189], v[62:63], v[192:193] op_sel_hi:[1,0]
	v_pk_mul_f32 v[190:191], v[64:65], v[192:193] op_sel_hi:[1,0]
	v_exp_f32_e32 v188, v188
	v_exp_f32_e32 v189, v189
	v_exp_f32_e32 v190, v190
	v_exp_f32_e32 v191, v191
	v_pk_add_f32 v[188:189], v[188:189], 1.0 op_sel_hi:[1,0]
	v_pk_add_f32 v[190:191], v[190:191], 1.0 op_sel_hi:[1,0]
	v_rcp_f32_e32 v188, v188
	v_rcp_f32_e32 v189, v189
	v_rcp_f32_e32 v190, v190
	v_rcp_f32_e32 v191, v191
	v_pk_mul_f32 v[62:63], v[62:63], v[188:189]
	v_pk_mul_f32 v[64:65], v[64:65], v[190:191]
	v_pk_mul_f32 v[54:55], v[54:55], v[62:63]
	v_pk_mul_f32 v[56:57], v[56:57], v[64:65]
	v_cvt_pk_bf16_f32 v184, v54, v55
	v_cvt_pk_bf16_f32 v185, v56, v57
	v_pk_mul_f32 v[188:189], v[58:59], v[192:193] op_sel_hi:[1,0]
	v_pk_mul_f32 v[190:191], v[60:61], v[192:193] op_sel_hi:[1,0]
	v_exp_f32_e32 v188, v188
	v_exp_f32_e32 v189, v189
	v_exp_f32_e32 v190, v190
	v_exp_f32_e32 v191, v191
	v_pk_add_f32 v[188:189], v[188:189], 1.0 op_sel_hi:[1,0]
	v_pk_add_f32 v[190:191], v[190:191], 1.0 op_sel_hi:[1,0]
	v_rcp_f32_e32 v188, v188
	v_rcp_f32_e32 v189, v189
	v_rcp_f32_e32 v190, v190
	v_rcp_f32_e32 v191, v191
	v_pk_mul_f32 v[58:59], v[58:59], v[188:189]
	v_pk_mul_f32 v[60:61], v[60:61], v[190:191]
	v_pk_mul_f32 v[50:51], v[50:51], v[58:59]
	v_pk_mul_f32 v[52:53], v[52:53], v[60:61]
	v_cvt_pk_bf16_f32 v186, v50, v51
	v_cvt_pk_bf16_f32 v187, v52, v53
	v_lshl_add_u64 v[182:183], v[182:183], 0, v[114:115]
	global_store_dwordx4 v[182:183], v[184:187], off
	v_ffbh_u32_e32 v180, v167
	v_min_u32_e32 v180, 32, v180
	v_lshlrev_b64 v[178:179], v180, v[166:167]
	v_min_u32_e32 v178, 1, v178
	v_or_b32_e32 v178, v179, v178
	v_cvt_f32_u32_e32 v178, v178
	v_sub_u32_e32 v179, 32, v180
	v_ldexp_f32 v178, v178, v179
	v_fmamk_f32 v178, v178, 0x31800000, v219
	v_rsq_f32_e32 v178, v178
	v_add_u32_e32 v181, 0x90, v142
	v_mad_i64_i32 v[182:183], s[22:23], v181, s83, v[146:147]
	v_pk_mul_f32 v[46:47], v[46:47], v[178:179] op_sel_hi:[1,0]
	v_pk_mul_f32 v[48:49], v[48:49], v[178:179] op_sel_hi:[1,0]
	v_pk_mul_f32 v[42:43], v[42:43], v[178:179] op_sel_hi:[1,0]
	v_pk_mul_f32 v[44:45], v[44:45], v[178:179] op_sel_hi:[1,0]
	v_pk_mul_f32 v[38:39], v[38:39], v[178:179] op_sel_hi:[1,0]
	v_pk_mul_f32 v[40:41], v[40:41], v[178:179] op_sel_hi:[1,0]
	v_pk_mul_f32 v[34:35], v[34:35], v[178:179] op_sel_hi:[1,0]
	v_pk_mul_f32 v[36:37], v[36:37], v[178:179] op_sel_hi:[1,0]
	v_pk_mul_f32 v[188:189], v[46:47], v[192:193] op_sel_hi:[1,0]
	v_pk_mul_f32 v[190:191], v[48:49], v[192:193] op_sel_hi:[1,0]
	v_exp_f32_e32 v188, v188
	v_exp_f32_e32 v189, v189
	v_exp_f32_e32 v190, v190
	v_exp_f32_e32 v191, v191
	v_pk_add_f32 v[188:189], v[188:189], 1.0 op_sel_hi:[1,0]
	v_pk_add_f32 v[190:191], v[190:191], 1.0 op_sel_hi:[1,0]
	v_rcp_f32_e32 v188, v188
	v_rcp_f32_e32 v189, v189
	v_rcp_f32_e32 v190, v190
	v_rcp_f32_e32 v191, v191
	v_pk_mul_f32 v[46:47], v[46:47], v[188:189]
	v_pk_mul_f32 v[48:49], v[48:49], v[190:191]
	v_pk_mul_f32 v[38:39], v[38:39], v[46:47]
	v_pk_mul_f32 v[40:41], v[40:41], v[48:49]
	v_cvt_pk_bf16_f32 v184, v38, v39
	v_cvt_pk_bf16_f32 v185, v40, v41
	v_pk_mul_f32 v[188:189], v[42:43], v[192:193] op_sel_hi:[1,0]
	v_pk_mul_f32 v[190:191], v[44:45], v[192:193] op_sel_hi:[1,0]
	v_exp_f32_e32 v188, v188
	v_exp_f32_e32 v189, v189
	v_exp_f32_e32 v190, v190
	v_exp_f32_e32 v191, v191
	v_pk_add_f32 v[188:189], v[188:189], 1.0 op_sel_hi:[1,0]
	v_pk_add_f32 v[190:191], v[190:191], 1.0 op_sel_hi:[1,0]
	v_rcp_f32_e32 v188, v188
	v_rcp_f32_e32 v189, v189
	v_rcp_f32_e32 v190, v190
	v_rcp_f32_e32 v191, v191
	v_pk_mul_f32 v[42:43], v[42:43], v[188:189]
	v_pk_mul_f32 v[44:45], v[44:45], v[190:191]
	v_pk_mul_f32 v[34:35], v[34:35], v[42:43]
	v_pk_mul_f32 v[36:37], v[36:37], v[44:45]
	v_cvt_pk_bf16_f32 v186, v34, v35
	v_cvt_pk_bf16_f32 v187, v36, v37
	v_lshl_add_u64 v[182:183], v[182:183], 0, v[114:115]
	global_store_dwordx4 v[182:183], v[184:187], off
	v_ffbh_u32_e32 v180, v169
	v_min_u32_e32 v180, 32, v180
	v_lshlrev_b64 v[178:179], v180, v[168:169]
	v_min_u32_e32 v178, 1, v178
	v_or_b32_e32 v178, v179, v178
	v_cvt_f32_u32_e32 v178, v178
	v_sub_u32_e32 v179, 32, v180
	v_ldexp_f32 v178, v178, v179
	v_fmamk_f32 v178, v178, 0x31800000, v219
	v_rsq_f32_e32 v178, v178
	v_add_u32_e32 v181, 0xa0, v142
	v_mad_i64_i32 v[182:183], s[22:23], v181, s83, v[146:147]
	v_pk_mul_f32 v[30:31], v[30:31], v[178:179] op_sel_hi:[1,0]
	v_pk_mul_f32 v[32:33], v[32:33], v[178:179] op_sel_hi:[1,0]
	v_pk_mul_f32 v[26:27], v[26:27], v[178:179] op_sel_hi:[1,0]
	v_pk_mul_f32 v[28:29], v[28:29], v[178:179] op_sel_hi:[1,0]
	v_pk_mul_f32 v[22:23], v[22:23], v[178:179] op_sel_hi:[1,0]
	v_pk_mul_f32 v[24:25], v[24:25], v[178:179] op_sel_hi:[1,0]
	v_pk_mul_f32 v[18:19], v[18:19], v[178:179] op_sel_hi:[1,0]
	v_pk_mul_f32 v[20:21], v[20:21], v[178:179] op_sel_hi:[1,0]
	v_pk_mul_f32 v[188:189], v[30:31], v[192:193] op_sel_hi:[1,0]
	v_pk_mul_f32 v[190:191], v[32:33], v[192:193] op_sel_hi:[1,0]
	v_exp_f32_e32 v188, v188
	v_exp_f32_e32 v189, v189
	v_exp_f32_e32 v190, v190
	v_exp_f32_e32 v191, v191
	v_pk_add_f32 v[188:189], v[188:189], 1.0 op_sel_hi:[1,0]
	v_pk_add_f32 v[190:191], v[190:191], 1.0 op_sel_hi:[1,0]
	v_rcp_f32_e32 v188, v188
	v_rcp_f32_e32 v189, v189
	v_rcp_f32_e32 v190, v190
	v_rcp_f32_e32 v191, v191
	v_pk_mul_f32 v[30:31], v[30:31], v[188:189]
	v_pk_mul_f32 v[32:33], v[32:33], v[190:191]
	v_pk_mul_f32 v[22:23], v[22:23], v[30:31]
	v_pk_mul_f32 v[24:25], v[24:25], v[32:33]
	v_cvt_pk_bf16_f32 v184, v22, v23
	v_cvt_pk_bf16_f32 v185, v24, v25
	v_pk_mul_f32 v[188:189], v[26:27], v[192:193] op_sel_hi:[1,0]
	v_pk_mul_f32 v[190:191], v[28:29], v[192:193] op_sel_hi:[1,0]
	v_exp_f32_e32 v188, v188
	v_exp_f32_e32 v189, v189
	v_exp_f32_e32 v190, v190
	v_exp_f32_e32 v191, v191
	v_pk_add_f32 v[188:189], v[188:189], 1.0 op_sel_hi:[1,0]
	v_pk_add_f32 v[190:191], v[190:191], 1.0 op_sel_hi:[1,0]
	v_rcp_f32_e32 v188, v188
	v_rcp_f32_e32 v189, v189
	v_rcp_f32_e32 v190, v190
	v_rcp_f32_e32 v191, v191
	v_pk_mul_f32 v[26:27], v[26:27], v[188:189]
	v_pk_mul_f32 v[28:29], v[28:29], v[190:191]
	v_pk_mul_f32 v[18:19], v[18:19], v[26:27]
	v_pk_mul_f32 v[20:21], v[20:21], v[28:29]
	v_cvt_pk_bf16_f32 v186, v18, v19
	v_cvt_pk_bf16_f32 v187, v20, v21
	v_lshl_add_u64 v[182:183], v[182:183], 0, v[114:115]
	global_store_dwordx4 v[182:183], v[184:187], off
	v_ffbh_u32_e32 v180, v171
	v_min_u32_e32 v180, 32, v180
	v_lshlrev_b64 v[178:179], v180, v[170:171]
	v_min_u32_e32 v178, 1, v178
	v_or_b32_e32 v178, v179, v178
	v_cvt_f32_u32_e32 v178, v178
	v_sub_u32_e32 v179, 32, v180
	v_ldexp_f32 v178, v178, v179
	v_fmamk_f32 v178, v178, 0x31800000, v219
	v_rsq_f32_e32 v178, v178
	v_add_u32_e32 v181, 0xb0, v142
	v_mad_i64_i32 v[182:183], s[22:23], v181, s83, v[146:147]
	s_andn2_b64 vcc, exec, s[2:3]
	v_pk_mul_f32 v[14:15], v[14:15], v[178:179] op_sel_hi:[1,0]
	v_pk_mul_f32 v[16:17], v[16:17], v[178:179] op_sel_hi:[1,0]
	v_pk_mul_f32 v[10:11], v[10:11], v[178:179] op_sel_hi:[1,0]
	v_pk_mul_f32 v[12:13], v[12:13], v[178:179] op_sel_hi:[1,0]
	v_pk_mul_f32 v[6:7], v[6:7], v[178:179] op_sel_hi:[1,0]
	v_pk_mul_f32 v[8:9], v[8:9], v[178:179] op_sel_hi:[1,0]
	v_pk_mul_f32 v[2:3], v[2:3], v[178:179] op_sel_hi:[1,0]
	v_pk_mul_f32 v[4:5], v[4:5], v[178:179] op_sel_hi:[1,0]
	s_mov_b64 s[22:23], -1
	v_pk_mul_f32 v[188:189], v[14:15], v[192:193] op_sel_hi:[1,0]
	v_pk_mul_f32 v[190:191], v[16:17], v[192:193] op_sel_hi:[1,0]
	v_exp_f32_e32 v188, v188
	v_exp_f32_e32 v189, v189
	v_exp_f32_e32 v190, v190
	v_exp_f32_e32 v191, v191
	v_pk_add_f32 v[188:189], v[188:189], 1.0 op_sel_hi:[1,0]
	v_pk_add_f32 v[190:191], v[190:191], 1.0 op_sel_hi:[1,0]
	v_rcp_f32_e32 v188, v188
	v_rcp_f32_e32 v189, v189
	v_rcp_f32_e32 v190, v190
	v_rcp_f32_e32 v191, v191
	v_pk_mul_f32 v[14:15], v[14:15], v[188:189]
	v_pk_mul_f32 v[16:17], v[16:17], v[190:191]
	v_pk_mul_f32 v[6:7], v[6:7], v[14:15]
	v_pk_mul_f32 v[8:9], v[8:9], v[16:17]
	v_cvt_pk_bf16_f32 v184, v6, v7
	v_cvt_pk_bf16_f32 v185, v8, v9
	v_pk_mul_f32 v[188:189], v[10:11], v[192:193] op_sel_hi:[1,0]
	v_pk_mul_f32 v[190:191], v[12:13], v[192:193] op_sel_hi:[1,0]
	v_exp_f32_e32 v188, v188
	v_exp_f32_e32 v189, v189
	v_exp_f32_e32 v190, v190
	v_exp_f32_e32 v191, v191
	v_pk_add_f32 v[188:189], v[188:189], 1.0 op_sel_hi:[1,0]
	v_pk_add_f32 v[190:191], v[190:191], 1.0 op_sel_hi:[1,0]
	v_rcp_f32_e32 v188, v188
	v_rcp_f32_e32 v189, v189
	v_rcp_f32_e32 v190, v190
	v_rcp_f32_e32 v191, v191
	v_pk_mul_f32 v[10:11], v[10:11], v[188:189]
	v_pk_mul_f32 v[12:13], v[12:13], v[190:191]
	v_pk_mul_f32 v[2:3], v[2:3], v[10:11]
	v_pk_mul_f32 v[4:5], v[4:5], v[12:13]
	v_cvt_pk_bf16_f32 v186, v2, v3
	v_cvt_pk_bf16_f32 v187, v4, v5
	v_lshl_add_u64 v[182:183], v[182:183], 0, v[114:115]
	global_store_dwordx4 v[182:183], v[184:187], off
	s_cbranch_vccnz .LBB0_1176
	s_andn2_b64 vcc, exec, s[6:7]
	s_cbranch_vccnz .LBB0_1175
	s_barrier
	s_branch .LBB0_1175
